# attention steady loops: packed f32 fma for the exp arguments and packed adds for the row sums
# baseline (speedup 1.0000x reference)
.Ldf_iter:
	v_mfma_f32_32x32x16_bf16 v[2:17], v[170:173], v[130:133], v[114:129]
	v_mfma_f32_32x32x16_bf16 v[18:33], v[170:173], v[138:141], v[114:129]
	v_mfma_f32_32x32x16_bf16 v[2:17], v[174:177], v[134:137], v[2:17]
	v_mfma_f32_32x32x16_bf16 v[18:33], v[174:177], v[142:145], v[18:33]
	v_mul_f32_e64 v220, -v200, v205
	v_fmamk_f32 v221, v200, 0xc2000000, v220
	v_add_f32_e32 v205, 0x42000000, v205
	s_nop 7
	v_max3_f32 v206, v2, v3, v4
	v_max3_f32 v207, v5, v6, v7
	v_max3_f32 v208, v8, v9, v10
	v_max3_f32 v209, v11, v12, v13
	v_max3_f32 v206, v206, v14, v15
	v_max3_f32 v207, v207, v16, v17
	v_max3_f32 v206, v206, v207, v208
	v_max_f32_e32 v206, v206, v209
	v_fma_f32 v206, v206, s98, v220
	v_mov_b32_e32 v207, v206
	s_nop 1
	v_permlane32_swap_b32_e32 v206, v207
	v_max3_f32 v194, v188, v206, v207
	v_sub_f32_e32 v208, v188, v194
	v_sub_f32_e32 v196, v220, v194
	v_exp_f32_e32 v190, v208
	v_pk_fma_f32 v[2:3], v[2:3], s[98:99], v[196:197] op_sel_hi:[1,0,0]
	v_pk_fma_f32 v[4:5], v[4:5], s[98:99], v[196:197] op_sel_hi:[1,0,0]
	v_pk_fma_f32 v[6:7], v[6:7], s[98:99], v[196:197] op_sel_hi:[1,0,0]
	v_pk_fma_f32 v[8:9], v[8:9], s[98:99], v[196:197] op_sel_hi:[1,0,0]
	v_pk_fma_f32 v[10:11], v[10:11], s[98:99], v[196:197] op_sel_hi:[1,0,0]
	v_pk_fma_f32 v[12:13], v[12:13], s[98:99], v[196:197] op_sel_hi:[1,0,0]
	v_pk_fma_f32 v[14:15], v[14:15], s[98:99], v[196:197] op_sel_hi:[1,0,0]
	v_pk_fma_f32 v[16:17], v[16:17], s[98:99], v[196:197] op_sel_hi:[1,0,0]
	v_exp_f32_e32 v2, v2
	v_exp_f32_e32 v3, v3
	v_exp_f32_e32 v4, v4
	v_exp_f32_e32 v5, v5
	v_exp_f32_e32 v6, v6
	v_exp_f32_e32 v7, v7
	v_exp_f32_e32 v8, v8
	v_exp_f32_e32 v9, v9
	v_exp_f32_e32 v10, v10
	v_exp_f32_e32 v11, v11
	v_exp_f32_e32 v12, v12
	v_exp_f32_e32 v13, v13
	v_exp_f32_e32 v14, v14
	v_exp_f32_e32 v15, v15
	v_exp_f32_e32 v16, v16
	v_exp_f32_e32 v17, v17
	v_cmp_lt_f32_e32 vcc, v188, v194
	v_mov_b32_e32 v188, v194
	v_cvt_pk_bf16_f32 v98, v2, v3
	v_cvt_pk_bf16_f32 v99, v4, v5
	v_cvt_pk_bf16_f32 v100, v6, v7
	v_cvt_pk_bf16_f32 v101, v8, v9
	v_cvt_pk_bf16_f32 v102, v10, v11
	v_cvt_pk_bf16_f32 v103, v12, v13
	v_cvt_pk_bf16_f32 v104, v14, v15
	v_cvt_pk_bf16_f32 v105, v16, v17
	v_pk_add_f32 v[2:3], v[2:3], v[4:5]
	v_pk_add_f32 v[6:7], v[6:7], v[8:9]
	v_pk_add_f32 v[10:11], v[10:11], v[12:13]
	v_pk_add_f32 v[14:15], v[14:15], v[16:17]
	v_pk_add_f32 v[2:3], v[2:3], v[6:7]
	v_pk_add_f32 v[10:11], v[10:11], v[14:15]
	v_pk_add_f32 v[2:3], v[2:3], v[10:11]
	v_add_f32_e32 v206, v2, v3
	v_fmac_f32_e32 v206, v182, v190
	v_mov_b32_e32 v182, v206
	s_cbranch_vccz .Ldf_nr0
	v_pk_mul_f32 v[82:83], v[82:83], v[190:191] op_sel_hi:[1,0]
	v_pk_mul_f32 v[84:85], v[84:85], v[190:191] op_sel_hi:[1,0]
	v_pk_mul_f32 v[86:87], v[86:87], v[190:191] op_sel_hi:[1,0]
	v_pk_mul_f32 v[88:89], v[88:89], v[190:191] op_sel_hi:[1,0]
	v_pk_mul_f32 v[90:91], v[90:91], v[190:191] op_sel_hi:[1,0]
	v_pk_mul_f32 v[92:93], v[92:93], v[190:191] op_sel_hi:[1,0]
	v_pk_mul_f32 v[94:95], v[94:95], v[190:191] op_sel_hi:[1,0]
	v_pk_mul_f32 v[96:97], v[96:97], v[190:191] op_sel_hi:[1,0]
	v_pk_mul_f32 v[66:67], v[66:67], v[190:191] op_sel_hi:[1,0]
	v_pk_mul_f32 v[68:69], v[68:69], v[190:191] op_sel_hi:[1,0]
	v_pk_mul_f32 v[70:71], v[70:71], v[190:191] op_sel_hi:[1,0]
	v_pk_mul_f32 v[72:73], v[72:73], v[190:191] op_sel_hi:[1,0]
	v_pk_mul_f32 v[74:75], v[74:75], v[190:191] op_sel_hi:[1,0]
	v_pk_mul_f32 v[76:77], v[76:77], v[190:191] op_sel_hi:[1,0]
	v_pk_mul_f32 v[78:79], v[78:79], v[190:191] op_sel_hi:[1,0]
	v_pk_mul_f32 v[80:81], v[80:81], v[190:191] op_sel_hi:[1,0]
	s_nop 1
.Ldf_nr0:
	s_waitcnt vmcnt(2)
	v_mfma_f32_32x32x16_bf16 v[82:97], v[166:169], v[98:101], v[82:97]
	v_mfma_f32_32x32x16_bf16 v[66:81], v[158:161], v[98:101], v[66:81]
	v_mfma_f32_32x32x16_bf16 v[82:97], v[162:165], v[102:105], v[82:97]
	v_mfma_f32_32x32x16_bf16 v[66:81], v[154:157], v[102:105], v[66:81]
	v_max3_f32 v210, v18, v19, v20
	v_max3_f32 v211, v21, v22, v23
	v_max3_f32 v215, v24, v25, v26
	v_max3_f32 v216, v27, v28, v29
	v_max3_f32 v210, v210, v30, v31
	v_max3_f32 v211, v211, v32, v33
	v_max3_f32 v210, v210, v211, v215
	v_max_f32_e32 v210, v210, v216
	v_fma_f32 v210, v210, s98, v221
	v_mov_b32_e32 v211, v210
	s_nop 1
	v_permlane32_swap_b32_e32 v210, v211
	v_max3_f32 v195, v0, v210, v211
	v_sub_f32_e32 v215, v0, v195
	v_sub_f32_e32 v198, v221, v195
	v_exp_f32_e32 v192, v215
	v_pk_fma_f32 v[18:19], v[18:19], s[98:99], v[198:199] op_sel_hi:[1,0,0]
	v_pk_fma_f32 v[20:21], v[20:21], s[98:99], v[198:199] op_sel_hi:[1,0,0]
	v_pk_fma_f32 v[22:23], v[22:23], s[98:99], v[198:199] op_sel_hi:[1,0,0]
	v_pk_fma_f32 v[24:25], v[24:25], s[98:99], v[198:199] op_sel_hi:[1,0,0]
	v_pk_fma_f32 v[26:27], v[26:27], s[98:99], v[198:199] op_sel_hi:[1,0,0]
	v_pk_fma_f32 v[28:29], v[28:29], s[98:99], v[198:199] op_sel_hi:[1,0,0]
	v_pk_fma_f32 v[30:31], v[30:31], s[98:99], v[198:199] op_sel_hi:[1,0,0]
	v_pk_fma_f32 v[32:33], v[32:33], s[98:99], v[198:199] op_sel_hi:[1,0,0]
	v_exp_f32_e32 v18, v18
	v_exp_f32_e32 v19, v19
	v_exp_f32_e32 v20, v20
	v_exp_f32_e32 v21, v21
	v_exp_f32_e32 v22, v22
	v_exp_f32_e32 v23, v23
	v_exp_f32_e32 v24, v24
	v_exp_f32_e32 v25, v25
	v_exp_f32_e32 v26, v26
	v_exp_f32_e32 v27, v27
	v_exp_f32_e32 v28, v28
	v_exp_f32_e32 v29, v29
	v_exp_f32_e32 v30, v30
	v_exp_f32_e32 v31, v31
	v_exp_f32_e32 v32, v32
	v_exp_f32_e32 v33, v33
	v_cmp_lt_f32_e32 vcc, v0, v195
	v_mov_b32_e32 v0, v195
	v_cvt_pk_bf16_f32 v106, v18, v19
	v_cvt_pk_bf16_f32 v107, v20, v21
	v_cvt_pk_bf16_f32 v108, v22, v23
	v_cvt_pk_bf16_f32 v109, v24, v25
	v_cvt_pk_bf16_f32 v110, v26, v27
	v_cvt_pk_bf16_f32 v111, v28, v29
	v_cvt_pk_bf16_f32 v112, v30, v31
	v_cvt_pk_bf16_f32 v113, v32, v33
	v_pk_add_f32 v[18:19], v[18:19], v[20:21]
	v_pk_add_f32 v[22:23], v[22:23], v[24:25]
	v_pk_add_f32 v[26:27], v[26:27], v[28:29]
	v_pk_add_f32 v[30:31], v[30:31], v[32:33]
	v_pk_add_f32 v[18:19], v[18:19], v[22:23]
	v_pk_add_f32 v[26:27], v[26:27], v[30:31]
	v_pk_add_f32 v[18:19], v[18:19], v[26:27]
	v_add_f32_e32 v210, v18, v19
	v_fmac_f32_e32 v210, v183, v192
	v_mov_b32_e32 v183, v210
	s_cbranch_vccz .Ldf_nr1
	v_pk_mul_f32 v[50:51], v[50:51], v[192:193] op_sel_hi:[1,0]
	v_pk_mul_f32 v[52:53], v[52:53], v[192:193] op_sel_hi:[1,0]
	v_pk_mul_f32 v[54:55], v[54:55], v[192:193] op_sel_hi:[1,0]
	v_pk_mul_f32 v[56:57], v[56:57], v[192:193] op_sel_hi:[1,0]
	v_pk_mul_f32 v[58:59], v[58:59], v[192:193] op_sel_hi:[1,0]
	v_pk_mul_f32 v[60:61], v[60:61], v[192:193] op_sel_hi:[1,0]
	v_pk_mul_f32 v[62:63], v[62:63], v[192:193] op_sel_hi:[1,0]
	v_pk_mul_f32 v[64:65], v[64:65], v[192:193] op_sel_hi:[1,0]
	v_pk_mul_f32 v[34:35], v[34:35], v[192:193] op_sel_hi:[1,0]
	v_pk_mul_f32 v[36:37], v[36:37], v[192:193] op_sel_hi:[1,0]
	v_pk_mul_f32 v[38:39], v[38:39], v[192:193] op_sel_hi:[1,0]
	v_pk_mul_f32 v[40:41], v[40:41], v[192:193] op_sel_hi:[1,0]
	v_pk_mul_f32 v[42:43], v[42:43], v[192:193] op_sel_hi:[1,0]
	v_pk_mul_f32 v[44:45], v[44:45], v[192:193] op_sel_hi:[1,0]
	v_pk_mul_f32 v[46:47], v[46:47], v[192:193] op_sel_hi:[1,0]
	v_pk_mul_f32 v[48:49], v[48:49], v[192:193] op_sel_hi:[1,0]
	s_nop 1
.Ldf_nr1:
	v_mfma_f32_32x32x16_bf16 v[50:65], v[166:169], v[106:109], v[50:65]
	v_mfma_f32_32x32x16_bf16 v[34:49], v[158:161], v[106:109], v[34:49]
	v_mfma_f32_32x32x16_bf16 v[50:65], v[162:165], v[110:113], v[50:65]
	v_mfma_f32_32x32x16_bf16 v[34:49], v[154:157], v[110:113], v[34:49]
	s_and_b64 vcc, exec, s[4:5]
	s_cbranch_vccnz .Ldf_exit
	s_add_i32 s15, s15, -1
	v_lshl_add_u64 v[180:181], v[180:181], 0, s[84:85]
	s_cmp_le_i32 s15, s73
	s_cselect_b64 s[4:5], -1, 0
	s_add_i32 s100, s15, -1
	s_cmp_le_i32 s15, s73
	s_cselect_b32 s76, s15, s100
	s_lshl_b64 s[16:17], s[76:77], 12
	s_waitcnt vmcnt(0)
	v_mov_b32_e32 v170, v146
	v_mov_b32_e32 v171, v147
	v_mov_b32_e32 v172, v148
	v_mov_b32_e32 v173, v149
	v_mov_b32_e32 v174, v150
	v_mov_b32_e32 v175, v151
	v_mov_b32_e32 v176, v152
	v_mov_b32_e32 v177, v153
	global_load_dwordx4 v[166:169], v[180:181], off offset:-2048
	global_load_dwordx4 v[162:165], v[180:181], off offset:-1024
	global_load_dwordx4 v[158:161], v[180:181], off
	global_load_dwordx4 v[154:157], v[180:181], off offset:1024
	v_lshl_add_u64 v[224:225], v[178:179], 0, s[16:17]
	global_load_dwordx4 v[146:149], v[224:225], off
	global_load_dwordx4 v[150:153], v[224:225], off offset:1024
	s_branch .Ldf_iter

.Lfx_iter:
	s_waitcnt lgkmcnt(0)
	v_mul_f32_e32 v114, 0x40b17218, v114
	v_mul_f32_e32 v115, 0x40b17218, v115
	v_mul_f32_e32 v116, 0x40b17218, v116
	v_mul_f32_e32 v117, 0x40b17218, v117
	v_mul_f32_e32 v118, 0x40b17218, v118
	v_mul_f32_e32 v119, 0x40b17218, v119
	v_mul_f32_e32 v120, 0x40b17218, v120
	v_mul_f32_e32 v121, 0x40b17218, v121
	v_mul_f32_e32 v122, 0x40b17218, v122
	v_mul_f32_e32 v123, 0x40b17218, v123
	v_mul_f32_e32 v124, 0x40b17218, v124
	v_mul_f32_e32 v125, 0x40b17218, v125
	v_mul_f32_e32 v126, 0x40b17218, v126
	v_mul_f32_e32 v127, 0x40b17218, v127
	v_mul_f32_e32 v128, 0x40b17218, v128
	v_mul_f32_e32 v129, 0x40b17218, v129
	s_nop 1
	v_mfma_f32_32x32x16_bf16 v[2:17], v[206:209], v[130:133], v[114:129]
	v_mfma_f32_32x32x16_bf16 v[18:33], v[206:209], v[146:149], v[114:129]
	v_mfma_f32_32x32x16_bf16 v[2:17], v[202:205], v[134:137], v[2:17]
	v_mfma_f32_32x32x16_bf16 v[18:33], v[202:205], v[150:153], v[18:33]
	v_mfma_f32_32x32x16_bf16 v[2:17], v[198:201], v[138:141], v[2:17]
	v_mfma_f32_32x32x16_bf16 v[18:33], v[198:201], v[154:157], v[18:33]
	v_mfma_f32_32x32x16_bf16 v[2:17], v[194:197], v[142:145], v[2:17]
	v_mfma_f32_32x32x16_bf16 v[18:33], v[194:197], v[158:161], v[18:33]
	s_nop 10
	v_max3_f32 v230, v2, v3, v4
	v_max3_f32 v231, v5, v6, v7
	v_max3_f32 v232, v8, v9, v10
	v_max3_f32 v233, v11, v12, v13
	v_max3_f32 v230, v230, v14, v15
	v_max3_f32 v231, v231, v16, v17
	v_max3_f32 v230, v230, v231, v232
	v_max_f32_e32 v230, v230, v233
	v_mul_f32_e32 v230, s98, v230
	v_mov_b32_e32 v231, v230
	s_nop 1
	v_permlane32_swap_b32_e32 v230, v231
	v_max3_f32 v220, v224, v230, v231
	v_sub_f32_e32 v232, v224, v220
	v_exp_f32_e32 v226, v232
	v_pk_fma_f32 v[2:3], v[2:3], s[98:99], v[220:221] op_sel_hi:[1,0,0] neg_lo:[0,0,1] neg_hi:[0,0,1]
	v_pk_fma_f32 v[4:5], v[4:5], s[98:99], v[220:221] op_sel_hi:[1,0,0] neg_lo:[0,0,1] neg_hi:[0,0,1]
	v_pk_fma_f32 v[6:7], v[6:7], s[98:99], v[220:221] op_sel_hi:[1,0,0] neg_lo:[0,0,1] neg_hi:[0,0,1]
	v_pk_fma_f32 v[8:9], v[8:9], s[98:99], v[220:221] op_sel_hi:[1,0,0] neg_lo:[0,0,1] neg_hi:[0,0,1]
	v_pk_fma_f32 v[10:11], v[10:11], s[98:99], v[220:221] op_sel_hi:[1,0,0] neg_lo:[0,0,1] neg_hi:[0,0,1]
	v_pk_fma_f32 v[12:13], v[12:13], s[98:99], v[220:221] op_sel_hi:[1,0,0] neg_lo:[0,0,1] neg_hi:[0,0,1]
	v_pk_fma_f32 v[14:15], v[14:15], s[98:99], v[220:221] op_sel_hi:[1,0,0] neg_lo:[0,0,1] neg_hi:[0,0,1]
	v_pk_fma_f32 v[16:17], v[16:17], s[98:99], v[220:221] op_sel_hi:[1,0,0] neg_lo:[0,0,1] neg_hi:[0,0,1]
	v_exp_f32_e32 v2, v2
	v_exp_f32_e32 v3, v3
	v_exp_f32_e32 v4, v4
	v_exp_f32_e32 v5, v5
	v_exp_f32_e32 v6, v6
	v_exp_f32_e32 v7, v7
	v_exp_f32_e32 v8, v8
	v_exp_f32_e32 v9, v9
	v_exp_f32_e32 v10, v10
	v_exp_f32_e32 v11, v11
	v_exp_f32_e32 v12, v12
	v_exp_f32_e32 v13, v13
	v_exp_f32_e32 v14, v14
	v_exp_f32_e32 v15, v15
	v_exp_f32_e32 v16, v16
	v_exp_f32_e32 v17, v17
	v_cmp_lt_f32_e32 vcc, v224, v220
	v_mov_b32_e32 v224, v220
	v_cvt_pk_bf16_f32 v98, v2, v3
	v_cvt_pk_bf16_f32 v99, v4, v5
	v_cvt_pk_bf16_f32 v100, v6, v7
	v_cvt_pk_bf16_f32 v101, v8, v9
	v_cvt_pk_bf16_f32 v102, v10, v11
	v_cvt_pk_bf16_f32 v103, v12, v13
	v_cvt_pk_bf16_f32 v104, v14, v15
	v_cvt_pk_bf16_f32 v105, v16, v17
	v_pk_add_f32 v[2:3], v[2:3], v[4:5]
	v_pk_add_f32 v[6:7], v[6:7], v[8:9]
	v_pk_add_f32 v[10:11], v[10:11], v[12:13]
	v_pk_add_f32 v[14:15], v[14:15], v[16:17]
	v_pk_add_f32 v[2:3], v[2:3], v[6:7]
	v_pk_add_f32 v[10:11], v[10:11], v[14:15]
	v_pk_add_f32 v[2:3], v[2:3], v[10:11]
	v_add_f32_e32 v230, v2, v3
	v_fmac_f32_e32 v230, v218, v226
	v_mov_b32_e32 v218, v230
	s_cbranch_vccz .Lfx_nr0
	v_pk_mul_f32 v[82:83], v[82:83], v[226:227] op_sel_hi:[1,0]
	v_pk_mul_f32 v[84:85], v[84:85], v[226:227] op_sel_hi:[1,0]
	v_pk_mul_f32 v[86:87], v[86:87], v[226:227] op_sel_hi:[1,0]
	v_pk_mul_f32 v[88:89], v[88:89], v[226:227] op_sel_hi:[1,0]
	v_pk_mul_f32 v[90:91], v[90:91], v[226:227] op_sel_hi:[1,0]
	v_pk_mul_f32 v[92:93], v[92:93], v[226:227] op_sel_hi:[1,0]
	v_pk_mul_f32 v[94:95], v[94:95], v[226:227] op_sel_hi:[1,0]
	v_pk_mul_f32 v[96:97], v[96:97], v[226:227] op_sel_hi:[1,0]
	v_pk_mul_f32 v[66:67], v[66:67], v[226:227] op_sel_hi:[1,0]
	v_pk_mul_f32 v[68:69], v[68:69], v[226:227] op_sel_hi:[1,0]
	v_pk_mul_f32 v[70:71], v[70:71], v[226:227] op_sel_hi:[1,0]
	v_pk_mul_f32 v[72:73], v[72:73], v[226:227] op_sel_hi:[1,0]
	v_pk_mul_f32 v[74:75], v[74:75], v[226:227] op_sel_hi:[1,0]
	v_pk_mul_f32 v[76:77], v[76:77], v[226:227] op_sel_hi:[1,0]
	v_pk_mul_f32 v[78:79], v[78:79], v[226:227] op_sel_hi:[1,0]
	v_pk_mul_f32 v[80:81], v[80:81], v[226:227] op_sel_hi:[1,0]
	s_nop 1
.Lfx_nr0:
	s_waitcnt vmcnt(4)
	v_mfma_f32_32x32x16_bf16 v[82:97], v[190:193], v[98:101], v[82:97]
	v_mfma_f32_32x32x16_bf16 v[66:81], v[182:185], v[98:101], v[66:81]
	v_mfma_f32_32x32x16_bf16 v[82:97], v[186:189], v[102:105], v[82:97]
	v_mfma_f32_32x32x16_bf16 v[66:81], v[178:181], v[102:105], v[66:81]
	v_max3_f32 v230, v18, v19, v20
	v_max3_f32 v231, v21, v22, v23
	v_max3_f32 v232, v24, v25, v26
	v_max3_f32 v233, v27, v28, v29
	v_max3_f32 v230, v230, v30, v31
	v_max3_f32 v231, v231, v32, v33
	v_max3_f32 v230, v230, v231, v232
	v_max_f32_e32 v230, v230, v233
	v_mul_f32_e32 v230, s98, v230
	v_mov_b32_e32 v231, v230
	s_nop 1
	v_permlane32_swap_b32_e32 v230, v231
	v_max3_f32 v222, v225, v230, v231
	v_sub_f32_e32 v232, v225, v222
	v_exp_f32_e32 v228, v232
	v_pk_fma_f32 v[18:19], v[18:19], s[98:99], v[222:223] op_sel_hi:[1,0,0] neg_lo:[0,0,1] neg_hi:[0,0,1]
	v_pk_fma_f32 v[20:21], v[20:21], s[98:99], v[222:223] op_sel_hi:[1,0,0] neg_lo:[0,0,1] neg_hi:[0,0,1]
	v_pk_fma_f32 v[22:23], v[22:23], s[98:99], v[222:223] op_sel_hi:[1,0,0] neg_lo:[0,0,1] neg_hi:[0,0,1]
	v_pk_fma_f32 v[24:25], v[24:25], s[98:99], v[222:223] op_sel_hi:[1,0,0] neg_lo:[0,0,1] neg_hi:[0,0,1]
	v_pk_fma_f32 v[26:27], v[26:27], s[98:99], v[222:223] op_sel_hi:[1,0,0] neg_lo:[0,0,1] neg_hi:[0,0,1]
	v_pk_fma_f32 v[28:29], v[28:29], s[98:99], v[222:223] op_sel_hi:[1,0,0] neg_lo:[0,0,1] neg_hi:[0,0,1]
	v_pk_fma_f32 v[30:31], v[30:31], s[98:99], v[222:223] op_sel_hi:[1,0,0] neg_lo:[0,0,1] neg_hi:[0,0,1]
	v_pk_fma_f32 v[32:33], v[32:33], s[98:99], v[222:223] op_sel_hi:[1,0,0] neg_lo:[0,0,1] neg_hi:[0,0,1]
	v_exp_f32_e32 v18, v18
	v_exp_f32_e32 v19, v19
	v_exp_f32_e32 v20, v20
	v_exp_f32_e32 v21, v21
	v_exp_f32_e32 v22, v22
	v_exp_f32_e32 v23, v23
	v_exp_f32_e32 v24, v24
	v_exp_f32_e32 v25, v25
	v_exp_f32_e32 v26, v26
	v_exp_f32_e32 v27, v27
	v_exp_f32_e32 v28, v28
	v_exp_f32_e32 v29, v29
	v_exp_f32_e32 v30, v30
	v_exp_f32_e32 v31, v31
	v_exp_f32_e32 v32, v32
	v_exp_f32_e32 v33, v33
	v_cmp_lt_f32_e32 vcc, v225, v222
	v_mov_b32_e32 v225, v222
	v_cvt_pk_bf16_f32 v106, v18, v19
	v_cvt_pk_bf16_f32 v107, v20, v21
	v_cvt_pk_bf16_f32 v108, v22, v23
	v_cvt_pk_bf16_f32 v109, v24, v25
	v_cvt_pk_bf16_f32 v110, v26, v27
	v_cvt_pk_bf16_f32 v111, v28, v29
	v_cvt_pk_bf16_f32 v112, v30, v31
	v_cvt_pk_bf16_f32 v113, v32, v33
	v_pk_add_f32 v[18:19], v[18:19], v[20:21]
	v_pk_add_f32 v[22:23], v[22:23], v[24:25]
	v_pk_add_f32 v[26:27], v[26:27], v[28:29]
	v_pk_add_f32 v[30:31], v[30:31], v[32:33]
	v_pk_add_f32 v[18:19], v[18:19], v[22:23]
	v_pk_add_f32 v[26:27], v[26:27], v[30:31]
	v_pk_add_f32 v[18:19], v[18:19], v[26:27]
	v_add_f32_e32 v230, v18, v19
	v_fmac_f32_e32 v230, v219, v228
	v_mov_b32_e32 v219, v230
	s_cbranch_vccz .Lfx_nr1
	v_pk_mul_f32 v[50:51], v[50:51], v[228:229] op_sel_hi:[1,0]
	v_pk_mul_f32 v[52:53], v[52:53], v[228:229] op_sel_hi:[1,0]
	v_pk_mul_f32 v[54:55], v[54:55], v[228:229] op_sel_hi:[1,0]
	v_pk_mul_f32 v[56:57], v[56:57], v[228:229] op_sel_hi:[1,0]
	v_pk_mul_f32 v[58:59], v[58:59], v[228:229] op_sel_hi:[1,0]
	v_pk_mul_f32 v[60:61], v[60:61], v[228:229] op_sel_hi:[1,0]
	v_pk_mul_f32 v[62:63], v[62:63], v[228:229] op_sel_hi:[1,0]
	v_pk_mul_f32 v[64:65], v[64:65], v[228:229] op_sel_hi:[1,0]
	v_pk_mul_f32 v[34:35], v[34:35], v[228:229] op_sel_hi:[1,0]
	v_pk_mul_f32 v[36:37], v[36:37], v[228:229] op_sel_hi:[1,0]
	v_pk_mul_f32 v[38:39], v[38:39], v[228:229] op_sel_hi:[1,0]
	v_pk_mul_f32 v[40:41], v[40:41], v[228:229] op_sel_hi:[1,0]
	v_pk_mul_f32 v[42:43], v[42:43], v[228:229] op_sel_hi:[1,0]
	v_pk_mul_f32 v[44:45], v[44:45], v[228:229] op_sel_hi:[1,0]
	v_pk_mul_f32 v[46:47], v[46:47], v[228:229] op_sel_hi:[1,0]
	v_pk_mul_f32 v[48:49], v[48:49], v[228:229] op_sel_hi:[1,0]
	s_nop 1
